# hand-written gdn_passC item loop with the four MFMA operand tiles staged once per workgroup through LDS
# speedup vs baseline: 1.0456x; 1.0014x over previous
.LBB0_794:
	v_and_b32_e32 v200, 15, v156
	v_bfe_u32 v201, v156, 4, 2
	v_bfe_u32 v202, v156, 6, 2
	v_lshrrev_b32_e32 v203, 8, v156
	v_lshl_or_b32 v204, v202, 4, v200
	v_lshlrev_b32_e32 v205, 4, v201
	v_lshl_add_u32 v206, v204, 8, v205
	v_lshl_add_u32 v207, v204, 7, v205
	v_lshl_add_u32 v208, v200, 8, v205
	v_lshl_or_b32 v209, v203, 6, v200
	v_lshl_add_u32 v209, v209, 7, v205
	v_add_u32_e32 v210, 0x1000, v209
	v_add_u32_e32 v211, 0x1000, v208
	v_add_u32_e32 v212, 0x2000, v208
	v_add_u32_e32 v213, 0x3000, v208
	v_lshlrev_b32_e32 v214, 2, v201
	v_lshl_or_b32 v214, v203, 6, v214
	v_mul_u32_u24_e32 v215, 0x3c00, v204
	v_lshl_add_u32 v215, v214, 1, v215
	v_lshlrev_b32_e32 v216, 2, v214
	v_and_b32_e32 v217, 63, v156
	v_xor_b32_e32 v218, 16, v217
	v_lshlrev_b32_e32 v218, 2, v218
	v_xor_b32_e32 v219, 32, v217
	v_lshlrev_b32_e32 v219, 2, v219
	v_lshlrev_b32_e32 v220, 3, v204
	v_lshl_add_u32 v221, v203, 2, v220
	v_mul_u32_u24_e32 v222, 0x110, v204
	v_lshl_add_u32 v222, v214, 1, v222
	v_add_u32_e32 v222, 0x400, v222
	v_lshrrev_b32_e32 v223, 4, v156
	v_and_b32_e32 v224, 15, v156
	v_mul_u32_u24_e32 v225, 0x110, v223
	v_lshl_add_u32 v225, v224, 4, v225
	v_add_u32_e32 v225, 0x400, v225
	v_mul_u32_u24_e32 v226, 0x3c00, v223
	v_lshl_add_u32 v226, v224, 4, v226
	v_add_u32_e32 v227, 0x78000, v226
	v_lshlrev_b32_e32 v229, 4, v156
	v_add_u32_e32 v230, 0x2000, v229
	v_lshrrev_b32_e32 v231, 4, v156
	v_mul_u32_u24_e32 v231, 0x110, v231
	v_lshl_add_u32 v231, v224, 4, v231
	v_lshrrev_b32_e32 v232, 3, v156
	v_mul_u32_u24_e32 v232, 0x90, v232
	v_and_b32_e32 v233, 7, v156
	v_lshl_add_u32 v232, v233, 4, v232
	v_mul_u32_u24_e32 v233, 0x110, v204
	v_add_u32_e32 v233, v233, v205
	v_mul_u32_u24_e32 v234, 0x90, v204
	v_add_u32_e32 v234, v234, v205
	v_lshl_or_b32 v235, v203, 6, v200
	v_mul_u32_u24_e32 v199, 0x90, v235
	v_add_u32_e32 v199, v199, v205
	v_add_u32_e32 v199, 0x13800, v199
	v_add_u32_e32 v198, 0x13800, v232
	v_add_u32_e32 v197, 0xb000, v231
	v_mul_u32_u24_e32 v235, 0x110, v235
	v_add_u32_e32 v235, v235, v205
	v_mov_b32_e32 v228, 0x358637bd
	v_readfirstlane_b32 s53, v203
.Lpassc_item:
	s_lshl_b32 s2, s51, 14
	s_add_u32 s8, s18, 0x127b0000
	s_addc_u32 s9, s19, 0
	s_add_u32 s8, s8, s2
	s_addc_u32 s9, s9, 0
	global_load_dwordx4 v[0:3], v229, s[8:9]
	global_load_dwordx4 v[4:7], v230, s[8:9]
	s_lshr_b32 s10, s2, 1
	s_add_u32 s26, s18, 0x137b0000
	s_addc_u32 s27, s19, 0
	s_add_u32 s26, s26, s10
	s_addc_u32 s27, s27, 0
	global_load_dwordx4 v[8:11], v229, s[26:27]
	s_add_u32 s8, s16, 0x3000000
	s_addc_u32 s9, s17, 0
	s_add_u32 s8, s8, s2
	s_addc_u32 s9, s9, 0
	global_load_dwordx4 v[12:15], v229, s[8:9]
	global_load_dwordx4 v[36:39], v230, s[8:9]
	s_add_u32 s8, s18, 0x117b0000
	s_addc_u32 s9, s19, 0
	s_add_u32 s8, s8, s2
	s_addc_u32 s9, s9, 0
	global_load_dwordx4 v[40:43], v229, s[8:9]
	global_load_dwordx4 v[44:47], v230, s[8:9]
	s_add_u32 s26, s16, 0x2000000
	s_addc_u32 s27, s17, 0
	s_add_u32 s26, s26, s2
	s_addc_u32 s27, s27, 0
	global_load_dwordx4 v[48:51], v229, s[26:27]
	global_load_dwordx4 v[52:55], v230, s[26:27]
	s_and_b32 s10, s51, 31
	s_lshr_b32 s30, s51, 7
	s_lshl_b32 s30, s30, 11
	s_lshl_b32 s10, s10, 6
	s_add_u32 s10, s10, s30
	s_mul_i32 s10, s10, 0x3c00
	s_bfe_u32 s30, s51, 0x20005
	s_lshl_b32 s30, s30, 8
	s_add_u32 s10, s10, s30
	s_add_u32 s38, s18, 0x2030000
	s_addc_u32 s39, s19, 0
	s_add_u32 s38, s38, s10
	s_addc_u32 s39, s39, 0
	s_add_u32 s8, s38, 0x1c00
	s_addc_u32 s9, s39, 0
	global_load_dwordx2 v[140:141], v215, s[8:9]
	global_load_dwordx2 v[142:143], v215, s[8:9] offset:32
	global_load_dwordx2 v[144:145], v215, s[8:9] offset:64
	global_load_dwordx2 v[146:147], v215, s[8:9] offset:96
	global_load_dwordx4 v[176:179], v216, s[6:7]
	global_load_dwordx4 v[180:183], v216, s[6:7] offset:64
	global_load_dwordx4 v[184:187], v216, s[6:7] offset:128
	global_load_dwordx4 v[188:191], v216, s[6:7] offset:192
	s_waitcnt vmcnt(8)
	ds_write_b128 v231, v[0:3] offset:18432
	ds_write_b128 v231, v[4:7] offset:27136
	ds_write_b128 v232, v[8:11] offset:35840
	ds_write_b128 v197, v[12:15]
	ds_write_b128 v197, v[36:39] offset:8704
	ds_write_b128 v197, v[40:43] offset:17408
	ds_write_b128 v197, v[44:47] offset:26112
	ds_write_b128 v198, v[48:51]
	ds_write_b128 v198, v[52:55] offset:9216
	s_waitcnt lgkmcnt(0)
	s_barrier
	ds_read_b128 v[0:3], v233 offset:18432
	ds_read_b128 v[4:7], v233 offset:18496
	ds_read_b128 v[8:11], v233 offset:18560
	ds_read_b128 v[12:15], v233 offset:18624
	ds_read_b128 v[36:39], v234 offset:35840
	ds_read_b128 v[40:43], v234 offset:35904
	ds_read_b128 v[44:47], v235 offset:45056
	ds_read_b128 v[48:51], v235 offset:45120
	ds_read_b128 v[52:55], v235 offset:45184
	ds_read_b128 v[56:59], v235 offset:45248
	ds_read_b128 v[108:111], v199 offset:0
	ds_read_b128 v[112:115], v199 offset:64
	ds_read_b128 v[60:63], v235 offset:49408
	ds_read_b128 v[64:67], v235 offset:49472
	ds_read_b128 v[68:71], v235 offset:49536
	ds_read_b128 v[72:75], v235 offset:49600
	ds_read_b128 v[116:119], v199 offset:2304
	ds_read_b128 v[120:123], v199 offset:2368
	ds_read_b128 v[76:79], v235 offset:53760
	ds_read_b128 v[80:83], v235 offset:53824
	ds_read_b128 v[84:87], v235 offset:53888
	ds_read_b128 v[88:91], v235 offset:53952
	ds_read_b128 v[124:127], v199 offset:4608
	ds_read_b128 v[128:131], v199 offset:4672
	ds_read_b128 v[92:95], v235 offset:58112
	ds_read_b128 v[96:99], v235 offset:58176
	ds_read_b128 v[100:103], v235 offset:58240
	ds_read_b128 v[104:107], v235 offset:58304
	ds_read_b128 v[132:135], v199 offset:6912
	ds_read_b128 v[136:139], v199 offset:6976
	s_waitcnt lgkmcnt(15)
	v_mfma_f32_16x16x32_bf16 v[160:163], v[44:47], v[0:3], 0
	v_mfma_f32_16x16x32_bf16 v[160:163], v[48:51], v[4:7], v[160:163]
	v_mfma_f32_16x16x32_bf16 v[160:163], v[52:55], v[8:11], v[160:163]
	v_mfma_f32_16x16x32_bf16 v[160:163], v[56:59], v[12:15], v[160:163]
	v_mfma_f32_16x16x32_bf16 v[160:163], v[108:111], v[36:39], v[160:163]
	v_mfma_f32_16x16x32_bf16 v[160:163], v[112:115], v[40:43], v[160:163]
	s_waitcnt lgkmcnt(12)
	v_mfma_f32_16x16x32_bf16 v[164:167], v[60:63], v[0:3], 0
	v_mfma_f32_16x16x32_bf16 v[164:167], v[64:67], v[4:7], v[164:167]
	v_mfma_f32_16x16x32_bf16 v[164:167], v[68:71], v[8:11], v[164:167]
	v_mfma_f32_16x16x32_bf16 v[164:167], v[72:75], v[12:15], v[164:167]
	v_mfma_f32_16x16x32_bf16 v[164:167], v[116:119], v[36:39], v[164:167]
	v_mfma_f32_16x16x32_bf16 v[164:167], v[120:123], v[40:43], v[164:167]
	s_waitcnt lgkmcnt(6)
	v_mfma_f32_16x16x32_bf16 v[168:171], v[76:79], v[0:3], 0
	v_mfma_f32_16x16x32_bf16 v[168:171], v[80:83], v[4:7], v[168:171]
	v_mfma_f32_16x16x32_bf16 v[168:171], v[84:87], v[8:11], v[168:171]
	v_mfma_f32_16x16x32_bf16 v[168:171], v[88:91], v[12:15], v[168:171]
	v_mfma_f32_16x16x32_bf16 v[168:171], v[124:127], v[36:39], v[168:171]
	v_mfma_f32_16x16x32_bf16 v[168:171], v[128:131], v[40:43], v[168:171]
	s_waitcnt lgkmcnt(0)
	v_mfma_f32_16x16x32_bf16 v[172:175], v[92:95], v[0:3], 0
	v_mfma_f32_16x16x32_bf16 v[172:175], v[96:99], v[4:7], v[172:175]
	v_mfma_f32_16x16x32_bf16 v[172:175], v[100:103], v[8:11], v[172:175]
	v_mfma_f32_16x16x32_bf16 v[172:175], v[104:107], v[12:15], v[172:175]
	v_mfma_f32_16x16x32_bf16 v[172:175], v[132:135], v[36:39], v[172:175]
	v_mfma_f32_16x16x32_bf16 v[172:175], v[136:139], v[40:43], v[172:175]
	s_nop 7
	s_nop 3
	v_mul_f32_e32 v192, v160, v160
	v_fmac_f32_e32 v192, v161, v161
	v_fmac_f32_e32 v192, v162, v162
	v_fmac_f32_e32 v192, v163, v163
	v_fmac_f32_e32 v192, v164, v164
	v_fmac_f32_e32 v192, v165, v165
	v_fmac_f32_e32 v192, v166, v166
	v_fmac_f32_e32 v192, v167, v167
	v_fmac_f32_e32 v192, v168, v168
	v_fmac_f32_e32 v192, v169, v169
	v_fmac_f32_e32 v192, v170, v170
	v_fmac_f32_e32 v192, v171, v171
	v_fmac_f32_e32 v192, v172, v172
	v_fmac_f32_e32 v192, v173, v173
	v_fmac_f32_e32 v192, v174, v174
	v_fmac_f32_e32 v192, v175, v175
	ds_bpermute_b32 v193, v218, v192
	s_waitcnt lgkmcnt(0)
	v_add_f32_e32 v192, v192, v193
	ds_bpermute_b32 v193, v219, v192
	s_waitcnt lgkmcnt(0)
	v_add_f32_e32 v192, v192, v193
	v_cmp_gt_u32_e32 vcc, 16, v217
	s_and_saveexec_b64 s[26:27], vcc
	ds_write_b32 v221, v192
	s_mov_b64 exec, s[26:27]
	s_waitcnt vmcnt(0)
	v_lshlrev_b32_e32 v124, 16, v140
	v_and_b32_e32 v125, 0xffff0000, v140
	v_lshlrev_b32_e32 v126, 16, v141
	v_and_b32_e32 v127, 0xffff0000, v141
	v_lshlrev_b32_e32 v128, 16, v142
	v_and_b32_e32 v129, 0xffff0000, v142
	v_lshlrev_b32_e32 v130, 16, v143
	v_and_b32_e32 v131, 0xffff0000, v143
	v_lshlrev_b32_e32 v132, 16, v144
	v_and_b32_e32 v133, 0xffff0000, v144
	v_lshlrev_b32_e32 v134, 16, v145
	v_and_b32_e32 v135, 0xffff0000, v145
	v_lshlrev_b32_e32 v136, 16, v146
	v_and_b32_e32 v137, 0xffff0000, v146
	v_lshlrev_b32_e32 v138, 16, v147
	v_and_b32_e32 v139, 0xffff0000, v147
	v_mul_f32_e32 v108, 0xbfb8aa3b, v124
	v_mul_f32_e32 v109, 0xbfb8aa3b, v125
	v_mul_f32_e32 v110, 0xbfb8aa3b, v126
	v_mul_f32_e32 v111, 0xbfb8aa3b, v127
	v_mul_f32_e32 v112, 0xbfb8aa3b, v128
	v_mul_f32_e32 v113, 0xbfb8aa3b, v129
	v_mul_f32_e32 v114, 0xbfb8aa3b, v130
	v_mul_f32_e32 v115, 0xbfb8aa3b, v131
	v_mul_f32_e32 v116, 0xbfb8aa3b, v132
	v_mul_f32_e32 v117, 0xbfb8aa3b, v133
	v_mul_f32_e32 v118, 0xbfb8aa3b, v134
	v_mul_f32_e32 v119, 0xbfb8aa3b, v135
	v_mul_f32_e32 v120, 0xbfb8aa3b, v136
	v_mul_f32_e32 v121, 0xbfb8aa3b, v137
	v_mul_f32_e32 v122, 0xbfb8aa3b, v138
	v_mul_f32_e32 v123, 0xbfb8aa3b, v139
	v_exp_f32_e32 v108, v108
	v_exp_f32_e32 v109, v109
	v_exp_f32_e32 v110, v110
	v_exp_f32_e32 v111, v111
	v_exp_f32_e32 v112, v112
	v_exp_f32_e32 v113, v113
	v_exp_f32_e32 v114, v114
	v_exp_f32_e32 v115, v115
	v_exp_f32_e32 v116, v116
	v_exp_f32_e32 v117, v117
	v_exp_f32_e32 v118, v118
	v_exp_f32_e32 v119, v119
	v_exp_f32_e32 v120, v120
	v_exp_f32_e32 v121, v121
	v_exp_f32_e32 v122, v122
	v_exp_f32_e32 v123, v123
	s_nop 0
	v_add_f32_e32 v108, 1.0, v108
	v_add_f32_e32 v109, 1.0, v109
	v_add_f32_e32 v110, 1.0, v110
	v_add_f32_e32 v111, 1.0, v111
	v_add_f32_e32 v112, 1.0, v112
	v_add_f32_e32 v113, 1.0, v113
	v_add_f32_e32 v114, 1.0, v114
	v_add_f32_e32 v115, 1.0, v115
	v_add_f32_e32 v116, 1.0, v116
	v_add_f32_e32 v117, 1.0, v117
	v_add_f32_e32 v118, 1.0, v118
	v_add_f32_e32 v119, 1.0, v119
	v_add_f32_e32 v120, 1.0, v120
	v_add_f32_e32 v121, 1.0, v121
	v_add_f32_e32 v122, 1.0, v122
	v_add_f32_e32 v123, 1.0, v123
	v_rcp_f32_e32 v108, v108
	v_rcp_f32_e32 v109, v109
	v_rcp_f32_e32 v110, v110
	v_rcp_f32_e32 v111, v111
	v_rcp_f32_e32 v112, v112
	v_rcp_f32_e32 v113, v113
	v_rcp_f32_e32 v114, v114
	v_rcp_f32_e32 v115, v115
	v_rcp_f32_e32 v116, v116
	v_rcp_f32_e32 v117, v117
	v_rcp_f32_e32 v118, v118
	v_rcp_f32_e32 v119, v119
	v_rcp_f32_e32 v120, v120
	v_rcp_f32_e32 v121, v121
	v_rcp_f32_e32 v122, v122
	v_rcp_f32_e32 v123, v123
	s_nop 0
	v_mul_f32_e32 v124, v124, v108
	v_mul_f32_e32 v125, v125, v109
	v_mul_f32_e32 v126, v126, v110
	v_mul_f32_e32 v127, v127, v111
	v_mul_f32_e32 v128, v128, v112
	v_mul_f32_e32 v129, v129, v113
	v_mul_f32_e32 v130, v130, v114
	v_mul_f32_e32 v131, v131, v115
	v_mul_f32_e32 v132, v132, v116
	v_mul_f32_e32 v133, v133, v117
	v_mul_f32_e32 v134, v134, v118
	v_mul_f32_e32 v135, v135, v119
	v_mul_f32_e32 v136, v136, v120
	v_mul_f32_e32 v137, v137, v121
	v_mul_f32_e32 v138, v138, v122
	v_mul_f32_e32 v139, v139, v123
	v_mul_f32_e32 v124, v124, v176
	v_mul_f32_e32 v125, v125, v177
	v_mul_f32_e32 v126, v126, v178
	v_mul_f32_e32 v127, v127, v179
	v_mul_f32_e32 v128, v128, v180
	v_mul_f32_e32 v129, v129, v181
	v_mul_f32_e32 v130, v130, v182
	v_mul_f32_e32 v131, v131, v183
	v_mul_f32_e32 v132, v132, v184
	v_mul_f32_e32 v133, v133, v185
	v_mul_f32_e32 v134, v134, v186
	v_mul_f32_e32 v135, v135, v187
	v_mul_f32_e32 v136, v136, v188
	v_mul_f32_e32 v137, v137, v189
	v_mul_f32_e32 v138, v138, v190
	v_mul_f32_e32 v139, v139, v191
	s_waitcnt lgkmcnt(0)
	s_barrier
	ds_read_b64 v[194:195], v220
	s_waitcnt lgkmcnt(0)
	v_add_f32_e32 v194, v194, v195
	v_fmamk_f32 v194, v194, 0x3c000000, v228
	v_rsq_f32_e32 v194, v194
	s_nop 0
	v_mul_f32_e32 v160, v160, v194
	v_mul_f32_e32 v161, v161, v194
	v_mul_f32_e32 v162, v162, v194
	v_mul_f32_e32 v163, v163, v194
	v_mul_f32_e32 v164, v164, v194
	v_mul_f32_e32 v165, v165, v194
	v_mul_f32_e32 v166, v166, v194
	v_mul_f32_e32 v167, v167, v194
	v_mul_f32_e32 v168, v168, v194
	v_mul_f32_e32 v169, v169, v194
	v_mul_f32_e32 v170, v170, v194
	v_mul_f32_e32 v171, v171, v194
	v_mul_f32_e32 v172, v172, v194
	v_mul_f32_e32 v173, v173, v194
	v_mul_f32_e32 v174, v174, v194
	v_mul_f32_e32 v175, v175, v194
	v_mul_f32_e32 v160, v160, v124
	v_mul_f32_e32 v161, v161, v125
	v_mul_f32_e32 v162, v162, v126
	v_mul_f32_e32 v163, v163, v127
	v_mul_f32_e32 v164, v164, v128
	v_mul_f32_e32 v165, v165, v129
	v_mul_f32_e32 v166, v166, v130
	v_mul_f32_e32 v167, v167, v131
	v_mul_f32_e32 v168, v168, v132
	v_mul_f32_e32 v169, v169, v133
	v_mul_f32_e32 v170, v170, v134
	v_mul_f32_e32 v171, v171, v135
	v_mul_f32_e32 v172, v172, v136
	v_mul_f32_e32 v173, v173, v137
	v_mul_f32_e32 v174, v174, v138
	v_mul_f32_e32 v175, v175, v139
	v_cvt_pk_bf16_f32 v108, v160, v161
	v_cvt_pk_bf16_f32 v109, v162, v163
	v_cvt_pk_bf16_f32 v110, v164, v165
	v_cvt_pk_bf16_f32 v111, v166, v167
	v_cvt_pk_bf16_f32 v112, v168, v169
	v_cvt_pk_bf16_f32 v113, v170, v171
	v_cvt_pk_bf16_f32 v114, v172, v173
	v_cvt_pk_bf16_f32 v115, v174, v175
	ds_write_b64 v222, v[108:109]
	ds_write_b64 v222, v[110:111] offset:32
	ds_write_b64 v222, v[112:113] offset:64
	ds_write_b64 v222, v[114:115] offset:96
	s_waitcnt lgkmcnt(0)
	s_barrier
	ds_read_b128 v[108:111], v225
	ds_read_b128 v[112:115], v225 offset:8704
	s_add_u32 s8, s38, 0x1000
	s_addc_u32 s9, s39, 0
	s_waitcnt lgkmcnt(1)
	global_store_dwordx4 v226, v[108:111], s[8:9]
	s_waitcnt lgkmcnt(0)
	global_store_dwordx4 v227, v[112:115], s[8:9]
	s_add_i32 s51, s51, s22
	s_cmpk_gt_i32 s51, 0x3ff
	s_cbranch_scc0 .Lpassc_item
	v_mov_b32_e32 v22, v218
	v_mov_b32_e32 v23, v219
	s_barrier
	s_branch .LBB0_796
